# v90 + nt on once-read streams: x loads in the prologue, sample carried-state loads and stores in the scan
# speedup vs baseline: 1.0105x; 1.0035x over previous
.LBB0_54:
	s_or_b64 exec, exec, s[8:9]
	s_waitcnt lgkmcnt(0)
	v_lshlrev_b64 v[6:7], 12, v[6:7]
	v_lshl_add_u64 v[6:7], v[8:9], 0, v[6:7]
	v_lshl_add_u64 v[10:11], v[6:7], 0, v[184:185]
	global_load_dwordx4 v[6:9], v[10:11], off nt
	v_ashrrev_i32_e32 v1, 31, v0
	v_lshlrev_b64 v[20:21], 11, v[0:1]
	v_lshl_add_u64 v[32:33], v[4:5], 0, v[20:21]
	s_waitcnt vmcnt(0)
	v_cvt_pk_bf16_f32 v20, v6, v7
	v_cvt_pk_bf16_f32 v21, v8, v9
	global_store_dwordx2 v[32:33], v[20:21], off
	global_load_dwordx4 v[20:23], v[10:11], off offset:1024 nt
	v_mul_f32_e32 v7, v7, v7
	v_mul_f32_e32 v9, v9, v9
	v_fmac_f32_e32 v7, v6, v6
	v_fmac_f32_e32 v9, v8, v8
	v_add_f32_e32 v6, v7, v9
	s_waitcnt vmcnt(0)
	v_cvt_pk_bf16_f32 v24, v20, v21
	v_cvt_pk_bf16_f32 v25, v22, v23
	global_store_dwordx2 v[32:33], v[24:25], off offset:512
	global_load_dwordx4 v[24:27], v[10:11], off offset:2048 nt
	v_mul_f32_e32 v7, v21, v21
	v_mul_f32_e32 v8, v23, v23
	v_fmac_f32_e32 v7, v20, v20
	v_fmac_f32_e32 v8, v22, v22
	v_add_f32_e32 v7, v7, v8
	v_add_f32_e32 v6, v6, v7
	s_waitcnt vmcnt(0)
	v_cvt_pk_bf16_f32 v28, v24, v25
	v_cvt_pk_bf16_f32 v29, v26, v27
	global_store_dwordx2 v[32:33], v[28:29], off offset:1024
	global_load_dwordx4 v[28:31], v[10:11], off offset:3072 nt
	v_mul_f32_e32 v7, v25, v25
	v_mul_f32_e32 v8, v27, v27
	v_fmac_f32_e32 v7, v24, v24
	v_fmac_f32_e32 v8, v26, v26
	v_add_f32_e32 v7, v7, v8
	v_add_f32_e32 v6, v6, v7
	s_waitcnt vmcnt(0)
	v_mul_f32_e32 v7, v29, v29
	v_mul_f32_e32 v8, v31, v31
	v_fmac_f32_e32 v7, v28, v28
	v_fmac_f32_e32 v8, v30, v30
	v_add_f32_e32 v7, v7, v8
	v_add_f32_e32 v6, v6, v7
	ds_bpermute_b32 v7, v13, v6
	v_cvt_pk_bf16_f32 v8, v28, v29
	v_cvt_pk_bf16_f32 v9, v30, v31
	global_store_dwordx2 v[32:33], v[8:9], off offset:1536
	s_waitcnt lgkmcnt(0)
	v_add_f32_e32 v6, v6, v7
	ds_bpermute_b32 v7, v14, v6
	s_waitcnt lgkmcnt(0)
	v_add_f32_e32 v6, v6, v7
	ds_bpermute_b32 v7, v15, v6
	s_waitcnt lgkmcnt(0)
	v_add_f32_e32 v6, v6, v7
	ds_bpermute_b32 v7, v16, v6
	s_waitcnt lgkmcnt(0)
	v_add_f32_e32 v6, v6, v7
	ds_bpermute_b32 v7, v17, v6
	s_waitcnt lgkmcnt(0)
	v_add_f32_e32 v6, v6, v7
	ds_bpermute_b32 v7, v18, v6
	s_and_saveexec_b64 s[8:9], vcc
	s_cbranch_execz .LBB0_45
	s_waitcnt lgkmcnt(0)
	v_add_f32_e32 v6, v6, v7
	v_cndmask_b32_e64 v8, 0, v6, s[0:1]
	v_lshlrev_b64 v[6:7], 6, v[0:1]
	v_lshl_add_u64 v[6:7], v[2:3], 0, v[6:7]
	global_store_dword v[6:7], v8, off
	s_branch .LBB0_45

.Lh_nopost:
	s_cmp_lt_u32 s12, 64
	s_cbranch_scc0 .Lh_nobuild
	s_add_i32 s13, s12, 1
	s_and_b32 s13, s13, 1
	s_waitcnt vmcnt(1)
	v_lshlrev_b32_e32 v84, 16, v52
	v_and_b32_e32 v85, 0xffff0000, v52
	v_lshlrev_b32_e32 v86, 16, v53
	v_and_b32_e32 v87, 0xffff0000, v53
	v_lshlrev_b32_e32 v88, 16, v54
	v_and_b32_e32 v89, 0xffff0000, v54
	v_lshlrev_b32_e32 v90, 16, v55
	v_and_b32_e32 v91, 0xffff0000, v55
	v_lshlrev_b32_e32 v124, 16, v64
	v_and_b32_e32 v125, 0xffff0000, v64
	v_lshlrev_b32_e32 v126, 16, v65
	v_and_b32_e32 v127, 0xffff0000, v65
	v_lshlrev_b32_e32 v128, 16, v66
	v_and_b32_e32 v129, 0xffff0000, v66
	v_lshlrev_b32_e32 v130, 16, v67
	v_and_b32_e32 v131, 0xffff0000, v67
	v_pk_add_f32 v[124:125], v[124:125], v[84:85] neg_lo:[0,1] neg_hi:[0,1]
	v_pk_add_f32 v[126:127], v[126:127], v[86:87] neg_lo:[0,1] neg_hi:[0,1]
	v_pk_add_f32 v[128:129], v[128:129], v[88:89] neg_lo:[0,1] neg_hi:[0,1]
	v_pk_add_f32 v[130:131], v[130:131], v[90:91] neg_lo:[0,1] neg_hi:[0,1]
	v_pk_fma_f32 v[84:85], v[0:1], v[124:125], v[84:85]
	v_pk_fma_f32 v[86:87], v[2:3], v[126:127], v[86:87]
	v_pk_fma_f32 v[88:89], v[4:5], v[128:129], v[88:89]
	v_pk_fma_f32 v[90:91], v[6:7], v[130:131], v[90:91]
	v_lshlrev_b32_e32 v92, 16, v56
	v_and_b32_e32 v93, 0xffff0000, v56
	v_lshlrev_b32_e32 v94, 16, v57
	v_and_b32_e32 v95, 0xffff0000, v57
	v_lshlrev_b32_e32 v96, 16, v58
	v_and_b32_e32 v97, 0xffff0000, v58
	v_lshlrev_b32_e32 v98, 16, v59
	v_and_b32_e32 v99, 0xffff0000, v59
	v_lshlrev_b32_e32 v124, 16, v68
	v_and_b32_e32 v125, 0xffff0000, v68
	v_lshlrev_b32_e32 v126, 16, v69
	v_and_b32_e32 v127, 0xffff0000, v69
	v_lshlrev_b32_e32 v128, 16, v70
	v_and_b32_e32 v129, 0xffff0000, v70
	v_lshlrev_b32_e32 v130, 16, v71
	v_and_b32_e32 v131, 0xffff0000, v71
	v_pk_add_f32 v[124:125], v[124:125], v[92:93] neg_lo:[0,1] neg_hi:[0,1]
	v_pk_add_f32 v[126:127], v[126:127], v[94:95] neg_lo:[0,1] neg_hi:[0,1]
	v_pk_add_f32 v[128:129], v[128:129], v[96:97] neg_lo:[0,1] neg_hi:[0,1]
	v_pk_add_f32 v[130:131], v[130:131], v[98:99] neg_lo:[0,1] neg_hi:[0,1]
	v_pk_fma_f32 v[92:93], v[8:9], v[124:125], v[92:93]
	v_pk_fma_f32 v[94:95], v[10:11], v[126:127], v[94:95]
	v_pk_fma_f32 v[96:97], v[12:13], v[128:129], v[96:97]
	v_pk_fma_f32 v[98:99], v[14:15], v[130:131], v[98:99]
	v_lshlrev_b32_e32 v100, 16, v60
	v_and_b32_e32 v101, 0xffff0000, v60
	v_lshlrev_b32_e32 v102, 16, v61
	v_and_b32_e32 v103, 0xffff0000, v61
	v_lshlrev_b32_e32 v104, 16, v62
	v_and_b32_e32 v105, 0xffff0000, v62
	v_lshlrev_b32_e32 v106, 16, v63
	v_and_b32_e32 v107, 0xffff0000, v63
	v_lshlrev_b32_e32 v124, 16, v72
	v_and_b32_e32 v125, 0xffff0000, v72
	v_lshlrev_b32_e32 v126, 16, v73
	v_and_b32_e32 v127, 0xffff0000, v73
	v_lshlrev_b32_e32 v128, 16, v74
	v_and_b32_e32 v129, 0xffff0000, v74
	v_lshlrev_b32_e32 v130, 16, v75
	v_and_b32_e32 v131, 0xffff0000, v75
	v_pk_add_f32 v[124:125], v[124:125], v[100:101] neg_lo:[0,1] neg_hi:[0,1]
	v_pk_add_f32 v[126:127], v[126:127], v[102:103] neg_lo:[0,1] neg_hi:[0,1]
	v_pk_add_f32 v[128:129], v[128:129], v[104:105] neg_lo:[0,1] neg_hi:[0,1]
	v_pk_add_f32 v[130:131], v[130:131], v[106:107] neg_lo:[0,1] neg_hi:[0,1]
	v_pk_fma_f32 v[100:101], v[16:17], v[124:125], v[100:101]
	v_pk_fma_f32 v[102:103], v[18:19], v[126:127], v[102:103]
	v_pk_fma_f32 v[104:105], v[20:21], v[128:129], v[104:105]
	v_pk_fma_f32 v[106:107], v[22:23], v[130:131], v[106:107]
	v_lshlrev_b32_e32 v108, 16, v80
	v_and_b32_e32 v109, 0xffff0000, v80
	v_lshlrev_b32_e32 v110, 16, v81
	v_and_b32_e32 v111, 0xffff0000, v81
	v_lshlrev_b32_e32 v112, 16, v82
	v_and_b32_e32 v113, 0xffff0000, v82
	v_lshlrev_b32_e32 v114, 16, v83
	v_and_b32_e32 v115, 0xffff0000, v83
	v_lshlrev_b32_e32 v116, 16, v76
	v_and_b32_e32 v117, 0xffff0000, v76
	v_lshlrev_b32_e32 v118, 16, v77
	v_and_b32_e32 v119, 0xffff0000, v77
	v_lshlrev_b32_e32 v120, 16, v78
	v_and_b32_e32 v121, 0xffff0000, v78
	v_lshlrev_b32_e32 v122, 16, v79
	v_and_b32_e32 v123, 0xffff0000, v79
	v_pk_mul_f32 v[132:133], v[92:93], v[24:25]
	v_pk_mul_f32 v[134:135], v[94:95], v[26:27]
	v_pk_mul_f32 v[136:137], v[96:97], v[28:29]
	v_pk_mul_f32 v[138:139], v[98:99], v[30:31]
	v_pk_add_f32 v[124:125], v[108:109], -1.0 op_sel_hi:[1,0]
	v_pk_add_f32 v[126:127], v[110:111], -1.0 op_sel_hi:[1,0]
	v_pk_add_f32 v[128:129], v[112:113], -1.0 op_sel_hi:[1,0]
	v_pk_add_f32 v[130:131], v[114:115], -1.0 op_sel_hi:[1,0]
	v_pk_fma_f32 v[124:125], v[32:33], v[124:125], 1.0 op_sel_hi:[1,1,0]
	v_pk_fma_f32 v[126:127], v[34:35], v[126:127], 1.0 op_sel_hi:[1,1,0]
	v_pk_fma_f32 v[128:129], v[36:37], v[128:129], 1.0 op_sel_hi:[1,1,0]
	v_pk_fma_f32 v[130:131], v[38:39], v[130:131], 1.0 op_sel_hi:[1,1,0]
	v_pk_mul_f32 v[140:141], v[124:125], v[92:93]
	v_pk_mul_f32 v[142:143], v[126:127], v[94:95]
	v_pk_mul_f32 v[144:145], v[128:129], v[96:97]
	v_pk_mul_f32 v[146:147], v[130:131], v[98:99]
	v_pk_mul_f32 v[148:149], v[84:85], v[140:141]
	v_pk_mul_f32 v[150:151], v[86:87], v[142:143]
	v_pk_mul_f32 v[152:153], v[88:89], v[144:145]
	v_pk_mul_f32 v[154:155], v[90:91], v[146:147]
	v_pk_mul_f32 v[156:157], v[132:133], v[108:109]
	v_pk_mul_f32 v[158:159], v[134:135], v[110:111]
	v_pk_mul_f32 v[160:161], v[136:137], v[112:113]
	v_pk_mul_f32 v[162:163], v[138:139], v[114:115]
	v_pk_mul_f32 v[124:125], v[148:149], v[40:41]
	v_pk_mul_f32 v[126:127], v[150:151], v[42:43]
	v_pk_mul_f32 v[128:129], v[152:153], v[44:45]
	v_pk_mul_f32 v[130:131], v[154:155], v[46:47]
	v_pk_add_f32 v[124:125], v[124:125], v[126:127]
	v_pk_add_f32 v[128:129], v[128:129], v[130:131]
	v_pk_add_f32 v[124:125], v[124:125], v[128:129]
	v_add_f32_e32 v173, v124, v125
	v_pk_mul_f32 v[124:125], v[156:157], v[84:85]
	v_pk_mul_f32 v[126:127], v[158:159], v[86:87]
	v_pk_mul_f32 v[128:129], v[160:161], v[88:89]
	v_pk_mul_f32 v[130:131], v[162:163], v[90:91]
	v_pk_add_f32 v[124:125], v[124:125], v[126:127]
	v_pk_add_f32 v[128:129], v[128:129], v[130:131]
	v_pk_add_f32 v[124:125], v[124:125], v[128:129]
	v_add_f32_e32 v174, v124, v125
	v_pk_mul_f32 v[124:125], v[132:133], v[132:133]
	v_pk_mul_f32 v[126:127], v[134:135], v[134:135]
	v_pk_mul_f32 v[128:129], v[136:137], v[136:137]
	v_pk_mul_f32 v[130:131], v[138:139], v[138:139]
	v_pk_add_f32 v[124:125], v[124:125], v[126:127]
	v_pk_add_f32 v[128:129], v[128:129], v[130:131]
	v_pk_add_f32 v[124:125], v[124:125], v[128:129]
	v_add_f32_e32 v172, v124, v125
	v_pk_add_f32 v[148:149], v[148:149], v[150:151]
	v_pk_add_f32 v[152:153], v[152:153], v[154:155]
	v_pk_add_f32 v[148:149], v[148:149], v[152:153]
	v_add_f32_e32 v175, v148, v149
	v_pk_mul_f32 v[116:117], v[116:117], v[48:49]
	v_pk_mul_f32 v[118:119], v[118:119], v[48:49]
	v_pk_mul_f32 v[120:121], v[120:121], v[48:49]
	v_pk_mul_f32 v[122:123], v[122:123], v[48:49]
	v_add_f32_dpp v172, v172, v172 quad_perm:[1,0,3,2] row_mask:0xf bank_mask:0xf bound_ctrl:1
	v_add_f32_dpp v173, v173, v173 quad_perm:[1,0,3,2] row_mask:0xf bank_mask:0xf bound_ctrl:1
	v_add_f32_dpp v174, v174, v174 quad_perm:[1,0,3,2] row_mask:0xf bank_mask:0xf bound_ctrl:1
	v_add_f32_dpp v175, v175, v175 quad_perm:[1,0,3,2] row_mask:0xf bank_mask:0xf bound_ctrl:1
	v_add_f32_dpp v172, v172, v172 quad_perm:[2,3,0,1] row_mask:0xf bank_mask:0xf bound_ctrl:1
	v_add_f32_dpp v173, v173, v173 quad_perm:[2,3,0,1] row_mask:0xf bank_mask:0xf bound_ctrl:1
	v_add_f32_dpp v174, v174, v174 quad_perm:[2,3,0,1] row_mask:0xf bank_mask:0xf bound_ctrl:1
	v_add_f32_dpp v175, v175, v175 quad_perm:[2,3,0,1] row_mask:0xf bank_mask:0xf bound_ctrl:1
	v_add_f32_dpp v172, v172, v172 row_half_mirror row_mask:0xf bank_mask:0xf bound_ctrl:1
	v_add_f32_dpp v173, v173, v173 row_half_mirror row_mask:0xf bank_mask:0xf bound_ctrl:1
	v_add_f32_dpp v174, v174, v174 row_half_mirror row_mask:0xf bank_mask:0xf bound_ctrl:1
	v_add_f32_dpp v175, v175, v175 row_half_mirror row_mask:0xf bank_mask:0xf bound_ctrl:1
	v_exp_f32_e32 v116, v116
	v_exp_f32_e32 v117, v117
	v_exp_f32_e32 v118, v118
	v_exp_f32_e32 v119, v119
	v_exp_f32_e32 v120, v120
	v_exp_f32_e32 v121, v121
	v_exp_f32_e32 v122, v122
	v_exp_f32_e32 v123, v123
	v_rsq_f32_e32 v176, v172
	v_pk_mul_f32 v[148:149], v[116:117], v[84:85]
	v_pk_mul_f32 v[150:151], v[118:119], v[86:87]
	v_pk_mul_f32 v[152:153], v[120:121], v[88:89]
	v_pk_mul_f32 v[154:155], v[122:123], v[90:91]
	v_min_f32_e32 v176, 0x5368d4a5, v176
	v_mul_f32_e32 v174, v174, v176
	v_pk_mul_f32 v[164:165], v[132:133], v[176:177] op_sel_hi:[1,0] neg_lo:[1,0] neg_hi:[1,0]
	v_pk_mul_f32 v[166:167], v[134:135], v[176:177] op_sel_hi:[1,0] neg_lo:[1,0] neg_hi:[1,0]
	v_pk_mul_f32 v[168:169], v[136:137], v[176:177] op_sel_hi:[1,0] neg_lo:[1,0] neg_hi:[1,0]
	v_pk_mul_f32 v[170:171], v[138:139], v[176:177] op_sel_hi:[1,0] neg_lo:[1,0] neg_hi:[1,0]
	v_pk_mul_f32 v[156:157], v[156:157], v[176:177] op_sel_hi:[1,0]
	v_pk_mul_f32 v[158:159], v[158:159], v[176:177] op_sel_hi:[1,0]
	v_pk_mul_f32 v[160:161], v[160:161], v[176:177] op_sel_hi:[1,0]
	v_pk_mul_f32 v[162:163], v[162:163], v[176:177] op_sel_hi:[1,0]
	s_mul_i32 s14, s13, 0xc000
	v_add_u32_e32 v198, s14, v194
	ds_write_b128 v198, v[148:151] offset:0
	ds_write_b128 v198, v[152:155] offset:128
	ds_write_b128 v198, v[116:119] offset:256
	ds_write_b128 v198, v[120:123] offset:384
	ds_write_b128 v198, v[140:143] offset:512
	ds_write_b128 v198, v[144:147] offset:640
	ds_write_b128 v198, v[164:167] offset:768
	ds_write_b128 v198, v[168:171] offset:896
	ds_write_b128 v198, v[156:159] offset:1024
	ds_write_b128 v198, v[160:163] offset:1152
	ds_write_b128 v198, v[100:103] offset:1280
	ds_write_b128 v198, v[104:107] offset:1408
	s_lshl_b32 s14, s13, 7
	v_add_u32_e32 v199, s14, v196
	s_lshl_b32 s14, s13, 8
	v_add_u32_e32 v198, s14, v197
	ds_write_b32 v199, v173
	ds_write_b64 v198, v[174:175]
	s_sub_u32 s0, s12, 1
	s_cmp_lt_u32 s0, 16
	s_cbranch_scc0 .Lhs_noproc
	s_mov_b32 s50, s0
	s_lshr_b32 s51, s50, 1
	s_and_b32 s52, s50, 1
	s_mul_i32 s53, s51, 0x600
	v_add_u32_e32 v198, s53, v238
	s_lshl_b32 s54, s52, 7
	s_add_i32 s53, s53, s54
	v_add_u32_e32 v199, s53, v239
	ds_read_b128 v[84:87], v198 offset:768
	ds_read_b128 v[88:91], v198 offset:896
	ds_read_b128 v[92:95], v198 offset:256
	ds_read_b128 v[96:99], v198 offset:384
	ds_read_b128 v[100:103], v198 offset:1024
	ds_read_b128 v[104:107], v198 offset:1152
	ds_read_b128 v[108:111], v198 offset:512
	ds_read_b128 v[112:115], v198 offset:640
	ds_read_b128 v[116:119], v198
	ds_read_b128 v[120:123], v198 offset:128
	ds_read_b32 v124, v199
	s_lshl_b32 s53, s51, 8
	s_add_i32 s53, s53, s54
	v_add_u32_e32 v205, s53, v240
	s_waitcnt lgkmcnt(0)
	v_pk_mul_f32 v[128:129], v[242:243], v[84:85]
	v_pk_fma_f32 v[128:129], v[244:245], v[86:87], v[128:129]
	v_pk_fma_f32 v[128:129], v[246:247], v[88:89], v[128:129]
	v_pk_fma_f32 v[128:129], v[248:249], v[90:91], v[128:129]
	v_add_f32_e32 v126, v128, v129
	v_pk_mul_f32 v[242:243], v[242:243], v[92:93]
	v_pk_mul_f32 v[244:245], v[244:245], v[94:95]
	v_pk_mul_f32 v[246:247], v[246:247], v[96:97]
	v_pk_mul_f32 v[248:249], v[248:249], v[98:99]
	v_add_f32_dpp v126, v126, v126 quad_perm:[1,0,3,2] row_mask:0xf bank_mask:0xf bound_ctrl:1
	s_nop 0
	s_nop 0
	v_add_f32_dpp v126, v126, v126 quad_perm:[2,3,0,1] row_mask:0xf bank_mask:0xf bound_ctrl:1
	s_nop 0
	s_nop 0
	v_add_f32_dpp v126, v126, v126 row_half_mirror row_mask:0xf bank_mask:0xf bound_ctrl:1
	v_pk_fma_f32 v[242:243], v[100:101], v[126:127], v[242:243] op_sel_hi:[1,0,1]
	v_pk_fma_f32 v[244:245], v[102:103], v[126:127], v[244:245] op_sel_hi:[1,0,1]
	v_pk_fma_f32 v[246:247], v[104:105], v[126:127], v[246:247] op_sel_hi:[1,0,1]
	v_pk_fma_f32 v[248:249], v[106:107], v[126:127], v[248:249] op_sel_hi:[1,0,1]
	v_pk_fma_f32 v[242:243], v[108:109], v[124:125], v[242:243] op_sel_hi:[1,0,1]
	v_pk_fma_f32 v[244:245], v[110:111], v[124:125], v[244:245] op_sel_hi:[1,0,1]
	v_pk_fma_f32 v[246:247], v[112:113], v[124:125], v[246:247] op_sel_hi:[1,0,1]
	v_pk_fma_f32 v[248:249], v[114:115], v[124:125], v[248:249] op_sel_hi:[1,0,1]
	v_pk_mul_f32 v[128:129], v[242:243], v[116:117]
	v_pk_fma_f32 v[128:129], v[244:245], v[118:119], v[128:129]
	v_pk_fma_f32 v[128:129], v[246:247], v[120:121], v[128:129]
	v_pk_fma_f32 v[128:129], v[248:249], v[122:123], v[128:129]
	v_add_f32_e32 v130, v128, v129
	global_store_dwordx4 v[236:237], v[242:245], off nt
	global_store_dwordx4 v[236:237], v[246:249], off offset:128 nt
	v_add_f32_dpp v130, v130, v130 quad_perm:[1,0,3,2] row_mask:0xf bank_mask:0xf bound_ctrl:1
	s_nop 0
	s_nop 0
	v_add_f32_dpp v130, v130, v130 quad_perm:[2,3,0,1] row_mask:0xf bank_mask:0xf bound_ctrl:1
	s_nop 0
	s_nop 0
	v_add_f32_dpp v130, v130, v130 row_half_mirror row_mask:0xf bank_mask:0xf bound_ctrl:1
	s_mov_b64 s[52:53], 0x2000
	v_lshl_add_u64 v[236:237], v[236:237], 0, s[52:53]
	ds_write_b32 v205, v130
.Lhs_noproc:
	s_cmp_lt_u32 s12, 16
	s_cbranch_scc0 .Lhs_noload
	global_load_dwordx4 v[242:245], v[250:251], off nt
	global_load_dwordx4 v[246:249], v[250:251], off offset:128 nt
	s_mov_b64 s[52:53], 0x2000
	v_lshl_add_u64 v[250:251], v[250:251], 0, s[52:53]
